# P8 epilogue second-half residual loads hoisted (no wait on the first half's write-through stores) on top of the write-through output stores
# baseline (speedup 1.0000x reference)
.LBB0_1092:
	v_lshl_or_b32 v128, s47, 8, v166
	v_lshl_add_u32 v160, s46, 8, v164
	s_ashr_i32 s20, s46, 3
	v_ashrrev_i32_e32 v129, 31, v128
	v_ashrrev_i32_e32 v161, 31, v160
	s_mul_hi_i32 s21, s20, 0xc000
	s_mul_i32 s20, s20, 0xc000
	v_lshl_add_u64 v[158:159], v[128:129], 1, s[28:29]
	v_lshlrev_b64 v[130:131], 12, v[160:161]
	s_add_u32 s20, s35, s20
	v_lshl_add_u64 v[130:131], v[158:159], 0, v[130:131]
	v_lshlrev_b64 v[156:157], 2, v[128:129]
	s_addc_u32 s21, s44, s21
	global_load_dwordx2 v[170:171], v[130:131], off nt
	global_load_dwordx2 v[172:173], v[130:131], off offset:32 nt
	global_load_dwordx2 v[176:177], v[130:131], off offset:288 nt
	v_lshl_add_u64 v[128:129], s[20:21], 0, v[156:157]
	v_or_b32_e32 v178, 16, v160
	global_load_dwordx2 v[174:175], v[130:131], off offset:256 nt
	global_load_dwordx4 v[132:135], v[128:129], off offset:512
	global_load_dwordx4 v[140:143], v[128:129], off
	global_load_dwordx4 v[136:139], v[128:129], off offset:64
	v_ashrrev_i32_e32 v179, 31, v178
	global_load_dwordx4 v[128:131], v[128:129], off offset:576
	v_lshlrev_b64 v[162:163], 12, v[178:179]
	v_lshl_add_u64 v[162:163], v[158:159], 0, v[162:163]
	global_load_dwordx2 v[180:181], v[162:163], off nt
	global_load_dwordx2 v[182:183], v[162:163], off offset:32 nt
	global_load_dwordx2 v[184:185], v[162:163], off offset:256 nt
	global_load_dwordx2 v[186:187], v[162:163], off offset:288 nt
	v_or_b32_e32 v188, 32, v160
	v_ashrrev_i32_e32 v189, 31, v188
	v_lshlrev_b64 v[162:163], 12, v[188:189]
	v_lshl_add_u64 v[190:191], v[158:159], 0, v[162:163]
	global_load_dwordx2 v[192:193], v[190:191], off nt
	global_load_dwordx2 v[196:197], v[190:191], off offset:32 nt
	v_or_b32_e32 v162, 48, v160
	v_ashrrev_i32_e32 v163, 31, v162
	v_lshlrev_b64 v[198:199], 12, v[162:163]
	v_lshl_add_u64 v[198:199], v[158:159], 0, v[198:199]
	global_load_dwordx2 v[200:201], v[190:191], off offset:256 nt
	s_nop 0
	global_load_dwordx2 v[190:191], v[190:191], off offset:288 nt
	s_nop 0
	global_load_dwordx2 v[202:203], v[198:199], off nt
	global_load_dwordx2 v[204:205], v[198:199], off offset:32 nt
	global_load_dwordx2 v[206:207], v[198:199], off offset:256 nt
	s_nop 0
	global_load_dwordx2 v[198:199], v[198:199], off offset:288 nt
	v_lshlrev_b64 v[194:195], 13, v[160:161]
	v_lshl_add_u64 v[194:195], s[6:7], 0, v[194:195]
	v_lshlrev_b64 v[178:179], 13, v[178:179]
	v_lshl_add_u64 v[194:195], v[194:195], 0, v[156:157]
	v_lshl_add_u64 v[178:179], s[6:7], 0, v[178:179]
	v_lshl_add_u64 v[178:179], v[178:179], 0, v[156:157]
	s_and_b64 vcc, exec, s[0:1]
	s_mov_b64 s[0:1], -1
	v_add_u32_e32 v208, 0x80, v160
	v_ashrrev_i32_e32 v209, 31, v208
	v_lshlrev_b64 v[208:209], 12, v[208:209]
	v_lshl_add_u64 v[208:209], v[158:159], 0, v[208:209]
	global_load_dwordx2 v[220:221], v[208:209], off nt
	global_load_dwordx2 v[222:223], v[208:209], off offset:32 nt
	global_load_dwordx2 v[224:225], v[208:209], off offset:256 nt
	global_load_dwordx2 v[226:227], v[208:209], off offset:288 nt
	v_add_u32_e32 v208, 0x90, v160
	v_ashrrev_i32_e32 v209, 31, v208
	v_lshlrev_b64 v[208:209], 12, v[208:209]
	v_lshl_add_u64 v[208:209], v[158:159], 0, v[208:209]
	global_load_dwordx2 v[228:229], v[208:209], off nt
	global_load_dwordx2 v[230:231], v[208:209], off offset:32 nt
	global_load_dwordx2 v[232:233], v[208:209], off offset:256 nt
	global_load_dwordx2 v[234:235], v[208:209], off offset:288 nt
	v_add_u32_e32 v208, 0xa0, v160
	v_ashrrev_i32_e32 v209, 31, v208
	v_lshlrev_b64 v[208:209], 12, v[208:209]
	v_lshl_add_u64 v[208:209], v[158:159], 0, v[208:209]
	global_load_dwordx2 v[236:237], v[208:209], off nt
	global_load_dwordx2 v[238:239], v[208:209], off offset:32 nt
	global_load_dwordx2 v[240:241], v[208:209], off offset:256 nt
	global_load_dwordx2 v[242:243], v[208:209], off offset:288 nt
	v_add_u32_e32 v208, 0xb0, v160
	v_ashrrev_i32_e32 v209, 31, v208
	v_lshlrev_b64 v[208:209], 12, v[208:209]
	v_lshl_add_u64 v[208:209], v[158:159], 0, v[208:209]
	global_load_dwordx2 v[244:245], v[208:209], off nt
	global_load_dwordx2 v[246:247], v[208:209], off offset:32 nt
	global_load_dwordx2 v[248:249], v[208:209], off offset:256 nt
	global_load_dwordx2 v[250:251], v[208:209], off offset:288 nt
	s_waitcnt vmcnt(0)
	v_lshlrev_b32_e32 v208, 16, v170
	v_and_b32_e32 v209, 0xffff0000, v170
	v_lshlrev_b32_e32 v170, 16, v171
	v_and_b32_e32 v171, 0xffff0000, v171
	v_lshlrev_b32_e32 v210, 16, v172
	v_and_b32_e32 v211, 0xffff0000, v172
	v_lshlrev_b32_e32 v172, 16, v173
	v_and_b32_e32 v173, 0xffff0000, v173
	v_lshlrev_b32_e32 v214, 16, v176
	v_and_b32_e32 v215, 0xffff0000, v176
	v_lshlrev_b32_e32 v176, 16, v177
	v_and_b32_e32 v177, 0xffff0000, v177
	v_lshlrev_b32_e32 v212, 16, v174
	v_and_b32_e32 v213, 0xffff0000, v174
	v_lshlrev_b32_e32 v174, 16, v175
	v_and_b32_e32 v175, 0xffff0000, v175
	v_pk_fma_f32 v[126:127], v[126:127], v[142:143], v[170:171]
	v_pk_fma_f32 v[124:125], v[124:125], v[140:141], v[208:209]
	v_pk_fma_f32 v[122:123], v[122:123], v[138:139], v[172:173]
	v_pk_fma_f32 v[110:111], v[110:111], v[130:131], v[176:177]
	v_pk_fma_f32 v[108:109], v[108:109], v[128:129], v[214:215]
	v_lshlrev_b32_e32 v170, 16, v180
	v_and_b32_e32 v171, 0xffff0000, v180
	v_lshlrev_b32_e32 v172, 16, v181
	v_and_b32_e32 v173, 0xffff0000, v181
	v_pk_fma_f32 v[120:121], v[120:121], v[136:137], v[210:211]
	v_pk_fma_f32 v[114:115], v[114:115], v[134:135], v[174:175]
	v_pk_fma_f32 v[112:113], v[112:113], v[132:133], v[212:213]
	flat_store_dwordx4 v[194:195], v[124:127] sc1
	flat_store_dwordx4 v[194:195], v[120:123] offset:64 sc1
	flat_store_dwordx4 v[194:195], v[112:115] offset:512 sc1
	flat_store_dwordx4 v[194:195], v[108:111] offset:576 sc1
	v_lshlrev_b32_e32 v174, 16, v182
	v_and_b32_e32 v175, 0xffff0000, v182
	v_pk_fma_f32 v[110:111], v[118:119], v[142:143], v[172:173]
	v_pk_fma_f32 v[108:109], v[116:117], v[140:141], v[170:171]
	flat_store_dwordx4 v[178:179], v[108:111] sc1
	v_pk_fma_f32 v[104:105], v[104:105], v[136:137], v[174:175]
	s_nop 0
	v_lshlrev_b32_e32 v108, 16, v183
	v_and_b32_e32 v109, 0xffff0000, v183
	v_pk_fma_f32 v[106:107], v[106:107], v[138:139], v[108:109]
	flat_store_dwordx4 v[178:179], v[104:107] offset:64 sc1
	s_nop 1
	v_lshlrev_b32_e32 v104, 16, v184
	v_and_b32_e32 v105, 0xffff0000, v184
	v_lshlrev_b32_e32 v106, 16, v185
	v_and_b32_e32 v107, 0xffff0000, v185
	v_pk_fma_f32 v[102:103], v[102:103], v[134:135], v[106:107]
	v_pk_fma_f32 v[100:101], v[100:101], v[132:133], v[104:105]
	flat_store_dwordx4 v[178:179], v[100:103] offset:512 sc1
	s_nop 1
	v_lshlrev_b32_e32 v100, 16, v186
	v_and_b32_e32 v101, 0xffff0000, v186
	v_lshlrev_b32_e32 v102, 16, v187
	v_and_b32_e32 v103, 0xffff0000, v187
	v_pk_fma_f32 v[94:95], v[94:95], v[130:131], v[102:103]
	v_pk_fma_f32 v[92:93], v[92:93], v[128:129], v[100:101]
	flat_store_dwordx4 v[178:179], v[92:95] offset:576 sc1
	s_nop 1
	v_lshlrev_b32_e32 v92, 16, v192
	v_and_b32_e32 v93, 0xffff0000, v192
	v_pk_fma_f32 v[92:93], v[96:97], v[140:141], v[92:93]
	v_lshlrev_b64 v[96:97], 13, v[188:189]
	v_lshlrev_b32_e32 v94, 16, v193
	v_and_b32_e32 v95, 0xffff0000, v193
	v_lshl_add_u64 v[96:97], s[6:7], 0, v[96:97]
	v_pk_fma_f32 v[94:95], v[98:99], v[142:143], v[94:95]
	v_lshl_add_u64 v[96:97], v[96:97], 0, v[156:157]
	flat_store_dwordx4 v[96:97], v[92:95] sc1
	v_add_u32_e32 v98, 0xb0, v160
	v_ashrrev_i32_e32 v99, 31, v98
	v_lshlrev_b32_e32 v92, 16, v196
	v_and_b32_e32 v93, 0xffff0000, v196
	v_lshlrev_b32_e32 v94, 16, v197
	v_and_b32_e32 v95, 0xffff0000, v197
	v_pk_fma_f32 v[90:91], v[90:91], v[138:139], v[94:95]
	v_pk_fma_f32 v[88:89], v[88:89], v[136:137], v[92:93]
	flat_store_dwordx4 v[96:97], v[88:91] offset:64 sc1
	s_nop 1
	v_lshlrev_b32_e32 v88, 16, v200
	v_and_b32_e32 v89, 0xffff0000, v200
	v_lshlrev_b32_e32 v90, 16, v201
	v_and_b32_e32 v91, 0xffff0000, v201
	v_pk_fma_f32 v[86:87], v[86:87], v[134:135], v[90:91]
	v_pk_fma_f32 v[84:85], v[84:85], v[132:133], v[88:89]
	flat_store_dwordx4 v[96:97], v[84:87] offset:512 sc1
	v_add_u32_e32 v88, 0xa0, v160
	v_ashrrev_i32_e32 v89, 31, v88
	v_lshlrev_b32_e32 v84, 16, v190
	v_and_b32_e32 v85, 0xffff0000, v190
	v_lshlrev_b32_e32 v86, 16, v191
	v_and_b32_e32 v87, 0xffff0000, v191
	v_pk_fma_f32 v[78:79], v[78:79], v[130:131], v[86:87]
	v_pk_fma_f32 v[76:77], v[76:77], v[128:129], v[84:85]
	flat_store_dwordx4 v[96:97], v[76:79] offset:576 sc1
	s_nop 1
	v_lshlrev_b32_e32 v76, 16, v202
	v_and_b32_e32 v77, 0xffff0000, v202
	v_pk_fma_f32 v[76:77], v[80:81], v[140:141], v[76:77]
	v_lshlrev_b64 v[80:81], 13, v[162:163]
	v_lshlrev_b32_e32 v78, 16, v203
	v_and_b32_e32 v79, 0xffff0000, v203
	v_lshl_add_u64 v[80:81], s[6:7], 0, v[80:81]
	v_pk_fma_f32 v[78:79], v[82:83], v[142:143], v[78:79]
	v_lshl_add_u64 v[80:81], v[80:81], 0, v[156:157]
	flat_store_dwordx4 v[80:81], v[76:79] sc1
	s_nop 1
	v_lshlrev_b32_e32 v76, 16, v204
	v_and_b32_e32 v77, 0xffff0000, v204
	v_lshlrev_b32_e32 v78, 16, v205
	v_and_b32_e32 v79, 0xffff0000, v205
	v_pk_fma_f32 v[74:75], v[74:75], v[138:139], v[78:79]
	v_pk_fma_f32 v[72:73], v[72:73], v[136:137], v[76:77]
	flat_store_dwordx4 v[80:81], v[72:75] offset:64 sc1
	v_add_u32_e32 v78, 0x90, v160
	v_ashrrev_i32_e32 v79, 31, v78
	v_lshlrev_b32_e32 v72, 16, v206
	v_and_b32_e32 v73, 0xffff0000, v206
	v_lshlrev_b32_e32 v74, 16, v207
	v_and_b32_e32 v75, 0xffff0000, v207
	v_pk_fma_f32 v[70:71], v[70:71], v[134:135], v[74:75]
	v_pk_fma_f32 v[68:69], v[68:69], v[132:133], v[72:73]
	flat_store_dwordx4 v[80:81], v[68:71] offset:512 sc1
	s_nop 1
	v_lshlrev_b32_e32 v68, 16, v198
	v_and_b32_e32 v69, 0xffff0000, v198
	v_lshlrev_b32_e32 v70, 16, v199
	v_and_b32_e32 v71, 0xffff0000, v199
	v_pk_fma_f32 v[64:65], v[64:65], v[128:129], v[68:69]
	v_add_u32_e32 v68, 0x80, v160
	v_pk_fma_f32 v[66:67], v[66:67], v[130:131], v[70:71]
	v_ashrrev_i32_e32 v69, 31, v68
	flat_store_dwordx4 v[80:81], v[64:67] offset:576 sc1
	s_nop 1
	v_lshlrev_b64 v[64:65], 12, v[68:69]
	v_lshl_add_u64 v[64:65], v[158:159], 0, v[64:65]
	v_mov_b64_e32 v[70:71], v[220:221]
	v_mov_b64_e32 v[72:73], v[222:223]
	v_mov_b64_e32 v[74:75], v[224:225]
	v_mov_b64_e32 v[76:77], v[226:227]
	v_lshlrev_b64 v[64:65], 12, v[78:79]
	v_lshl_add_u64 v[64:65], v[158:159], 0, v[64:65]
	v_mov_b64_e32 v[80:81], v[228:229]
	v_mov_b64_e32 v[82:83], v[230:231]
	v_mov_b64_e32 v[84:85], v[232:233]
	v_mov_b64_e32 v[86:87], v[234:235]
	v_lshlrev_b64 v[64:65], 12, v[88:89]
	v_lshl_add_u64 v[64:65], v[158:159], 0, v[64:65]
	v_mov_b64_e32 v[90:91], v[236:237]
	v_mov_b64_e32 v[92:93], v[238:239]
	v_mov_b64_e32 v[94:95], v[240:241]
	v_mov_b64_e32 v[96:97], v[242:243]
	v_lshlrev_b64 v[64:65], 12, v[98:99]
	v_lshl_add_u64 v[64:65], v[158:159], 0, v[64:65]
	v_mov_b64_e32 v[100:101], v[244:245]
	v_mov_b64_e32 v[102:103], v[246:247]
	v_mov_b64_e32 v[66:67], v[248:249]
	s_nop 0
	v_mov_b64_e32 v[64:65], v[250:251]
	v_lshlrev_b64 v[68:69], 13, v[68:69]
	v_lshl_add_u64 v[68:69], s[6:7], 0, v[68:69]
	v_lshl_add_u64 v[68:69], v[68:69], 0, v[156:157]
	s_nop 0
	v_lshlrev_b32_e32 v104, 16, v70
	v_and_b32_e32 v105, 0xffff0000, v70
	v_lshlrev_b32_e32 v70, 16, v71
	v_and_b32_e32 v71, 0xffff0000, v71
	v_pk_fma_f32 v[62:63], v[62:63], v[142:143], v[70:71]
	v_pk_fma_f32 v[60:61], v[60:61], v[140:141], v[104:105]
	flat_store_dwordx4 v[68:69], v[60:63] sc1
	s_nop 1
	v_lshlrev_b32_e32 v60, 16, v72
	v_and_b32_e32 v61, 0xffff0000, v72
	v_lshlrev_b32_e32 v62, 16, v73
	v_and_b32_e32 v63, 0xffff0000, v73
	v_pk_fma_f32 v[58:59], v[58:59], v[138:139], v[62:63]
	v_pk_fma_f32 v[56:57], v[56:57], v[136:137], v[60:61]
	flat_store_dwordx4 v[68:69], v[56:59] offset:64 sc1
	s_nop 1
	v_lshlrev_b32_e32 v56, 16, v74
	v_and_b32_e32 v57, 0xffff0000, v74
	v_lshlrev_b32_e32 v58, 16, v75
	v_and_b32_e32 v59, 0xffff0000, v75
	v_pk_fma_f32 v[54:55], v[54:55], v[134:135], v[58:59]
	v_pk_fma_f32 v[52:53], v[52:53], v[132:133], v[56:57]
	flat_store_dwordx4 v[68:69], v[52:55] offset:512 sc1
	s_nop 1
	v_lshlrev_b32_e32 v52, 16, v76
	v_and_b32_e32 v53, 0xffff0000, v76
	v_lshlrev_b32_e32 v54, 16, v77
	v_and_b32_e32 v55, 0xffff0000, v77
	v_pk_fma_f32 v[46:47], v[46:47], v[130:131], v[54:55]
	v_pk_fma_f32 v[44:45], v[44:45], v[128:129], v[52:53]
	flat_store_dwordx4 v[68:69], v[44:47] offset:576 sc1
	s_nop 1
	v_lshlrev_b32_e32 v44, 16, v80
	v_and_b32_e32 v45, 0xffff0000, v80
	v_pk_fma_f32 v[44:45], v[48:49], v[140:141], v[44:45]
	v_lshlrev_b64 v[48:49], 13, v[78:79]
	v_lshlrev_b32_e32 v46, 16, v81
	v_and_b32_e32 v47, 0xffff0000, v81
	v_lshl_add_u64 v[48:49], s[6:7], 0, v[48:49]
	v_pk_fma_f32 v[46:47], v[50:51], v[142:143], v[46:47]
	v_lshl_add_u64 v[48:49], v[48:49], 0, v[156:157]
	flat_store_dwordx4 v[48:49], v[44:47] sc1
	s_nop 1
	v_lshlrev_b32_e32 v44, 16, v82
	v_and_b32_e32 v45, 0xffff0000, v82
	v_lshlrev_b32_e32 v46, 16, v83
	v_and_b32_e32 v47, 0xffff0000, v83
	v_pk_fma_f32 v[42:43], v[42:43], v[138:139], v[46:47]
	v_pk_fma_f32 v[40:41], v[40:41], v[136:137], v[44:45]
	flat_store_dwordx4 v[48:49], v[40:43] offset:64 sc1
	s_nop 1
	v_lshlrev_b32_e32 v40, 16, v84
	v_and_b32_e32 v41, 0xffff0000, v84
	v_lshlrev_b32_e32 v42, 16, v85
	v_and_b32_e32 v43, 0xffff0000, v85
	v_pk_fma_f32 v[38:39], v[38:39], v[134:135], v[42:43]
	v_pk_fma_f32 v[36:37], v[36:37], v[132:133], v[40:41]
	flat_store_dwordx4 v[48:49], v[36:39] offset:512 sc1
	s_nop 1
	v_lshlrev_b32_e32 v36, 16, v86
	v_and_b32_e32 v37, 0xffff0000, v86
	v_lshlrev_b32_e32 v38, 16, v87
	v_and_b32_e32 v39, 0xffff0000, v87
	v_pk_fma_f32 v[30:31], v[30:31], v[130:131], v[38:39]
	v_pk_fma_f32 v[28:29], v[28:29], v[128:129], v[36:37]
	flat_store_dwordx4 v[48:49], v[28:31] offset:576 sc1
	s_nop 1
	v_lshlrev_b32_e32 v28, 16, v90
	v_and_b32_e32 v29, 0xffff0000, v90
	v_pk_fma_f32 v[28:29], v[32:33], v[140:141], v[28:29]
	v_lshlrev_b64 v[32:33], 13, v[88:89]
	v_lshlrev_b32_e32 v30, 16, v91
	v_and_b32_e32 v31, 0xffff0000, v91
	v_lshl_add_u64 v[32:33], s[6:7], 0, v[32:33]
	v_pk_fma_f32 v[30:31], v[34:35], v[142:143], v[30:31]
	v_lshl_add_u64 v[32:33], v[32:33], 0, v[156:157]
	flat_store_dwordx4 v[32:33], v[28:31] sc1
	s_nop 1
	v_lshlrev_b32_e32 v28, 16, v92
	v_and_b32_e32 v29, 0xffff0000, v92
	v_lshlrev_b32_e32 v30, 16, v93
	v_and_b32_e32 v31, 0xffff0000, v93
	v_pk_fma_f32 v[26:27], v[26:27], v[138:139], v[30:31]
	v_pk_fma_f32 v[24:25], v[24:25], v[136:137], v[28:29]
	flat_store_dwordx4 v[32:33], v[24:27] offset:64 sc1
	s_nop 1
	v_lshlrev_b32_e32 v24, 16, v94
	v_and_b32_e32 v25, 0xffff0000, v94
	v_lshlrev_b32_e32 v26, 16, v95
	v_and_b32_e32 v27, 0xffff0000, v95
	v_pk_fma_f32 v[22:23], v[22:23], v[134:135], v[26:27]
	v_pk_fma_f32 v[20:21], v[20:21], v[132:133], v[24:25]
	flat_store_dwordx4 v[32:33], v[20:23] offset:512 sc1
	s_nop 1
	v_lshlrev_b32_e32 v20, 16, v96
	v_and_b32_e32 v21, 0xffff0000, v96
	v_lshlrev_b32_e32 v22, 16, v97
	v_and_b32_e32 v23, 0xffff0000, v97
	v_pk_fma_f32 v[14:15], v[14:15], v[130:131], v[22:23]
	v_pk_fma_f32 v[12:13], v[12:13], v[128:129], v[20:21]
	flat_store_dwordx4 v[32:33], v[12:15] offset:576 sc1
	s_nop 1
	v_lshlrev_b32_e32 v12, 16, v100
	v_and_b32_e32 v13, 0xffff0000, v100
	v_pk_fma_f32 v[12:13], v[16:17], v[140:141], v[12:13]
	v_lshlrev_b64 v[16:17], 13, v[98:99]
	v_lshlrev_b32_e32 v14, 16, v101
	v_and_b32_e32 v15, 0xffff0000, v101
	v_lshl_add_u64 v[16:17], s[6:7], 0, v[16:17]
	v_pk_fma_f32 v[14:15], v[18:19], v[142:143], v[14:15]
	v_lshl_add_u64 v[16:17], v[16:17], 0, v[156:157]
	flat_store_dwordx4 v[16:17], v[12:15] sc1
	s_nop 1
	v_lshlrev_b32_e32 v12, 16, v102
	v_and_b32_e32 v13, 0xffff0000, v102
	v_lshlrev_b32_e32 v14, 16, v103
	v_and_b32_e32 v15, 0xffff0000, v103
	v_pk_fma_f32 v[10:11], v[10:11], v[138:139], v[14:15]
	v_pk_fma_f32 v[8:9], v[8:9], v[136:137], v[12:13]
	flat_store_dwordx4 v[16:17], v[8:11] offset:64 sc1
	s_nop 1
	v_lshlrev_b32_e32 v8, 16, v66
	v_and_b32_e32 v9, 0xffff0000, v66
	v_lshlrev_b32_e32 v10, 16, v67
	v_and_b32_e32 v11, 0xffff0000, v67
	v_pk_fma_f32 v[6:7], v[6:7], v[134:135], v[10:11]
	v_pk_fma_f32 v[4:5], v[4:5], v[132:133], v[8:9]
	flat_store_dwordx4 v[16:17], v[4:7] offset:512 sc1
	s_nop 1
	v_lshlrev_b32_e32 v4, 16, v64
	v_and_b32_e32 v5, 0xffff0000, v64
	v_lshlrev_b32_e32 v6, 16, v65
	v_and_b32_e32 v7, 0xffff0000, v65
	v_pk_fma_f32 v[2:3], v[2:3], v[130:131], v[6:7]
	v_pk_fma_f32 v[0:1], v[0:1], v[128:129], v[4:5]
	flat_store_dwordx4 v[16:17], v[0:3] offset:576 sc1
	s_cbranch_vccnz .LBB0_1077
	s_andn2_b64 vcc, exec, s[12:13]
	s_cbranch_vccnz .LBB0_1076
	s_barrier
	s_branch .LBB0_1076
